# conv sweep loops: removed adjacent no-op s_setprio 1/0 pairs
# baseline (speedup 1.0000x reference)
; template <int NQ, int NB, int L>
; __device__ __forceinline__ void conv_unit(LAS unsigned char* lds, const Args& a, int j, int seq0, int c, int tid) {
;     ...
;         const int dl_a = mw + 3 * GS - S_HI, dl_b = mw - S_LO;
;         static_assert(((3 * GS / 32) % 2 == 0) && (((S_HI - S_LO - 3 * GS) / 32 + 1) % 2 == 1), "conv step-count parity");
; #pragma unroll 1
;         for (int dl = d_lo; dl < dl_a; dl += 64) { CONV_STEP(Bc, Bn, dl, true); CONV_STEP(Bn, Bc, dl + 32, true); }
; #pragma unroll 1
;         for (int dl = dl_a; dl < dl_b; dl += 64) { CONV_STEP(Bc, Bn, dl, false); CONV_STEP(Bn, Bc, dl + 32, false); }
;         CONV_STEP(Bc, Bn, dl_b, false);
; #pragma unroll 1
;         for (int dl = dl_b + 32; dl <= d_hi; dl += 64) { CONV_STEP(Bn, Bc, dl, true); CONV_STEP(Bc, Bn, dl + 32, true); }
.LBB0_1341:
	v_add_u32_e32 v135, v32, v194
	s_waitcnt lgkmcnt(3)
	v_mfma_f32_16x16x32_bf16 v[60:63], v[70:73], v[82:85], v[90:93]
	v_add_u32_e32 v136, v134, v194
	s_mov_b32 s56, s71
	v_mfma_f32_16x16x32_bf16 v[64:67], v[74:77], v[82:85], v[86:89]
	v_add_u32_e32 v90, 0x1704a, v135
	s_waitcnt lgkmcnt(1)
	v_mfma_f32_16x16x32_bf16 v[34:37], v[78:81], v[24:27], v[36:39]
	v_add_u32_e32 v86, 0x1706a, v135
	v_add_u32_e32 v87, 0x1703e, v135
	v_add_u32_e32 v88, 0x17042, v135
	v_add_u32_e32 v38, 0x1705e, v135
	v_mfma_f32_16x16x32_bf16 v[52:55], v[16:19], v[82:85], v[52:55]
	v_add_u32_e32 v39, 0x17062, v135
	v_mfma_f32_16x16x32_bf16 v[56:59], v[78:81], v[82:85], v[94:97]
	v_mfma_f32_16x16x32_bf16 v[40:43], v[16:19], v[106:109], v[40:43]
	v_mfma_f32_16x16x32_bf16 v[28:31], v[78:81], v[106:109], v[28:31]
	v_mfma_f32_16x16x32_bf16 v[44:47], v[70:73], v[106:109], v[44:47]
	v_mfma_f32_16x16x32_bf16 v[48:51], v[74:77], v[106:109], v[48:51]
	ds_read_b128 v[82:85], v136 offset:8576
	ds_read_b128 v[106:109], v136 offset:8832
	ds_read_b128 v[130:133], v136 offset:9088
	ds_read_b128 v[148:151], v136 offset:9344
	v_mfma_f32_16x16x32_bf16 v[20:23], v[16:19], v[24:27], v[20:23]
	v_mfma_f32_16x16x32_bf16 v[102:105], v[70:73], v[24:27], v[102:105]
	v_mfma_f32_16x16x32_bf16 v[98:101], v[74:77], v[24:27], v[98:101]
	s_waitcnt lgkmcnt(4)
	v_mfma_f32_16x16x32_bf16 v[24:27], v[16:19], v[110:113], v[114:117]
	ds_read2_b32 v[16:17], v38 offset1:1
	ds_read2_b32 v[68:69], v39 offset1:1
	ds_read2_b32 v[18:19], v86 offset1:1
	ds_read2_b32 v[86:87], v87 offset1:1
	ds_read2_b32 v[88:89], v88 offset1:1
	ds_read2_b32 v[90:91], v90 offset1:1
	v_mfma_f32_16x16x32_bf16 v[78:81], v[78:81], v[110:113], v[118:121]
	v_mfma_f32_16x16x32_bf16 v[122:125], v[70:73], v[110:113], v[122:125]
	v_mfma_f32_16x16x32_bf16 v[126:129], v[74:77], v[110:113], v[126:129]
	s_waitcnt lgkmcnt(3)
	v_alignbit_b32 v19, v19, v18, v15
	v_alignbit_b32 v18, v18, v69, v14
	v_alignbit_b32 v17, v69, v17, v13
	v_alignbit_b32 v16, v68, v16, v12
	v_mfma_f32_16x16x32_bf16 v[118:121], v[74:77], v[148:151], v[78:81]
	s_waitcnt lgkmcnt(0)
	s_nop 1
	v_alignbit_b32 v81, v91, v90, v15
	v_alignbit_b32 v80, v90, v89, v14
	v_alignbit_b32 v79, v89, v87, v13
	v_alignbit_b32 v78, v88, v86, v12
	v_mfma_f32_16x16x32_bf16 v[94:97], v[74:77], v[82:85], v[56:59]
	v_mfma_f32_16x16x32_bf16 v[36:39], v[74:77], v[130:133], v[34:37]
	s_nop 1
	v_add_u32_e32 v56, 0x17022, v135
	v_add_u32_e32 v58, 0x1702a, v135
	v_mfma_f32_16x16x32_bf16 v[90:93], v[16:19], v[82:85], v[60:63]
	v_add_u32_e32 v34, 0x1701e, v135
	v_mfma_f32_16x16x32_bf16 v[86:89], v[78:81], v[82:85], v[64:67]
	s_nop 0
	v_add_u32_e32 v60, 0x16ffe, v135
	v_add_u32_e32 v62, 0x17002, v135
	v_add_u32_e32 v64, 0x1700a, v135
	v_mfma_f32_16x16x32_bf16 v[52:55], v[70:73], v[82:85], v[52:55]
	ds_read_b128 v[82:85], v136 offset:8512
	v_mfma_f32_16x16x32_bf16 v[40:43], v[70:73], v[106:109], v[40:43]
	v_mfma_f32_16x16x32_bf16 v[28:31], v[74:77], v[106:109], v[28:31]
	v_mfma_f32_16x16x32_bf16 v[114:117], v[70:73], v[148:151], v[24:27]
	v_mfma_f32_16x16x32_bf16 v[44:47], v[16:19], v[106:109], v[44:47]
	v_mfma_f32_16x16x32_bf16 v[48:51], v[78:81], v[106:109], v[48:51]
	ds_read_b128 v[106:109], v136 offset:8768
	ds_read_b128 v[24:27], v136 offset:9024
	ds_read_b128 v[110:113], v136 offset:9280
	ds_read2_b32 v[34:35], v34 offset1:1
	ds_read2_b32 v[56:57], v56 offset1:1
	ds_read2_b32 v[58:59], v58 offset1:1
	ds_read2_b32 v[60:61], v60 offset1:1
	ds_read2_b32 v[62:63], v62 offset1:1
	ds_read2_b32 v[64:65], v64 offset1:1
	v_mfma_f32_16x16x32_bf16 v[20:23], v[70:73], v[130:133], v[20:23]
	s_waitcnt lgkmcnt(4)
	v_alignbit_b32 v71, v57, v35, v13
	s_waitcnt lgkmcnt(3)
	v_alignbit_b32 v73, v59, v58, v15
	v_mfma_f32_16x16x32_bf16 v[102:105], v[16:19], v[130:133], v[102:105]
	v_alignbit_b32 v72, v58, v57, v14
	v_alignbit_b32 v70, v56, v34, v12
	v_mfma_f32_16x16x32_bf16 v[98:101], v[78:81], v[130:133], v[98:101]
	v_mfma_f32_16x16x32_bf16 v[122:125], v[16:19], v[148:151], v[122:125]
	v_mfma_f32_16x16x32_bf16 v[126:129], v[78:81], v[148:151], v[126:129]
	s_add_i32 s94, s94, 64
	s_addk_i32 s71, 0xff80
	s_waitcnt lgkmcnt(0)
	v_alignbit_b32 v77, v65, v64, v15
	v_alignbit_b32 v76, v64, v63, v14
	v_alignbit_b32 v75, v63, v61, v13
	v_alignbit_b32 v74, v62, v60, v12
	v_add_u32_e32 v134, 0xffffff80, v134
	s_cmp_gt_i32 s94, s50
	v_add_u32_e32 v32, 0xffffff80, v32
	s_cbranch_scc0 .LBB0_1341
	v_mfma_f32_16x16x32_bf16 v[66:69], v[16:19], v[82:85], v[52:55]
	v_add_u32_e32 v32, s75, v193
	v_mfma_f32_16x16x32_bf16 v[54:57], v[70:73], v[106:109], v[44:47]
	v_mfma_f32_16x16x32_bf16 v[50:53], v[74:77], v[106:109], v[48:51]
	v_mfma_f32_16x16x32_bf16 v[46:49], v[16:19], v[24:27], v[20:23]
	s_nop 2
	v_add_u32_e32 v20, v134, v194
	v_add_u32_e32 v21, s83, v193
	v_mfma_f32_16x16x32_bf16 v[62:65], v[16:19], v[106:109], v[40:43]
	v_mfma_f32_16x16x32_bf16 v[58:61], v[78:81], v[106:109], v[28:31]
	v_mfma_f32_16x16x32_bf16 v[42:45], v[78:81], v[24:27], v[36:39]
	v_mfma_f32_16x16x32_bf16 v[34:37], v[70:73], v[24:27], v[102:105]
	v_mfma_f32_16x16x32_bf16 v[24:27], v[74:77], v[24:27], v[98:101]
	ds_read_b128 v[130:133], v20 offset:8832
	s_nop 1
	ds_read_b128 v[98:101], v20 offset:9088
	v_mfma_f32_16x16x32_bf16 v[38:41], v[16:19], v[110:113], v[114:117]
	ds_read2_b32 v[16:17], v21 offset0:1 offset1:2
	ds_read2_b32 v[18:19], v21 offset0:3 offset1:4
	ds_read2_b32 v[106:107], v32 offset1:1
	ds_read2_b32 v[102:103], v21 offset1:1
	ds_read_b128 v[114:117], v20 offset:9344
	s_waitcnt lgkmcnt(3)
	v_alignbit_b32 v105, v19, v18, v15
	v_mfma_f32_16x16x32_bf16 v[28:31], v[78:81], v[110:113], v[118:121]
	s_nop 2
	ds_read2_b32 v[118:119], v32 offset0:1 offset1:2
	ds_read2_b32 v[108:109], v32 offset0:3 offset1:4
	v_alignbit_b32 v104, v18, v17, v14
	s_waitcnt lgkmcnt(3)
	v_alignbit_b32 v103, v17, v103, v13
	v_mfma_f32_16x16x32_bf16 v[20:23], v[70:73], v[110:113], v[122:125]
	v_alignbit_b32 v102, v16, v102, v12
	v_mfma_f32_16x16x32_bf16 v[16:19], v[74:77], v[110:113], v[126:129]
	s_waitcnt lgkmcnt(0)
	v_alignbit_b32 v109, v109, v108, v15
	v_alignbit_b32 v108, v108, v119, v14
	v_alignbit_b32 v107, v119, v107, v13
	v_alignbit_b32 v106, v118, v106, v12
	v_mov_b64_e32 v[112:113], v[72:73]
	v_mov_b64_e32 v[120:121], v[76:77]
	s_movk_i32 s71, 0xc0
	v_mov_b32_e32 v32, v216
	s_mov_b32 s94, s92
	v_mov_b64_e32 v[110:111], v[70:71]
	v_mov_b64_e32 v[118:119], v[74:75]
	s_branch .LBB0_1344

; template <int NQ, int NB, int L>
; __device__ __forceinline__ void conv_unit(LAS unsigned char* lds, const Args& a, int j, int seq0, int c, int tid) {
;     ...
;         const int dl_a = mw + 3 * GS - S_HI, dl_b = mw - S_LO;
;         static_assert(((3 * GS / 32) % 2 == 0) && (((S_HI - S_LO - 3 * GS) / 32 + 1) % 2 == 1), "conv step-count parity");
; #pragma unroll 1
;         for (int dl = d_lo; dl < dl_a; dl += 64) { CONV_STEP(Bc, Bn, dl, true); CONV_STEP(Bn, Bc, dl + 32, true); }
; #pragma unroll 1
;         for (int dl = dl_a; dl < dl_b; dl += 64) { CONV_STEP(Bc, Bn, dl, false); CONV_STEP(Bn, Bc, dl + 32, false); }
;         CONV_STEP(Bc, Bn, dl_b, false);
; #pragma unroll 1
;         for (int dl = dl_b + 32; dl <= d_hi; dl += 64) { CONV_STEP(Bn, Bc, dl, true); CONV_STEP(Bc, Bn, dl + 32, true); }
.LBB0_1546:
	v_add_u32_e32 v143, v32, v217
	s_waitcnt lgkmcnt(3)
	v_mfma_f32_16x16x32_bf16 v[68:71], v[78:81], v[90:93], v[94:97]
	v_add_u32_e32 v76, 0x1ad5e, v143
	v_add_u32_e32 v77, 0x1ad6a, v143
	v_add_u32_e32 v144, v142, v217
	s_waitcnt lgkmcnt(1)
	v_mfma_f32_16x16x32_bf16 v[28:31], v[24:27], v[36:39], v[28:31]
	v_add_u32_e32 v94, 0x1ad3e, v143
	v_add_u32_e32 v95, 0x1ad42, v143
	v_add_u32_e32 v96, 0x1ad4a, v143
	v_mfma_f32_16x16x32_bf16 v[44:47], v[86:89], v[36:39], v[44:47]
	s_mov_b32 s49, s56
	v_mfma_f32_16x16x32_bf16 v[110:113], v[78:81], v[36:39], v[110:113]
	v_mfma_f32_16x16x32_bf16 v[106:109], v[82:85], v[36:39], v[106:109]
	v_add_u32_e32 v38, 0x1ad62, v143
	v_mfma_f32_16x16x32_bf16 v[60:63], v[24:27], v[90:93], v[60:63]
	v_mfma_f32_16x16x32_bf16 v[64:67], v[86:89], v[90:93], v[102:105]
	v_mfma_f32_16x16x32_bf16 v[72:75], v[82:85], v[90:93], v[98:101]
	v_mfma_f32_16x16x32_bf16 v[48:51], v[24:27], v[114:117], v[48:51]
	v_mfma_f32_16x16x32_bf16 v[40:43], v[86:89], v[114:117], v[40:43]
	v_mfma_f32_16x16x32_bf16 v[52:55], v[78:81], v[114:117], v[52:55]
	v_mfma_f32_16x16x32_bf16 v[56:59], v[82:85], v[114:117], v[56:59]
	ds_read_b128 v[90:93], v144 offset:16768
	ds_read_b128 v[114:117], v144 offset:17280
	ds_read_b128 v[138:141], v144 offset:17792
	ds_read_b128 v[178:181], v144 offset:18304
	s_waitcnt lgkmcnt(4)
	v_mfma_f32_16x16x32_bf16 v[34:37], v[24:27], v[118:121], v[122:125]
	ds_read2_b32 v[24:25], v76 offset1:1
	ds_read2_b32 v[38:39], v38 offset1:1
	ds_read2_b32 v[26:27], v77 offset1:1
	ds_read2_b32 v[76:77], v94 offset1:1
	ds_read2_b32 v[98:99], v95 offset1:1
	ds_read2_b32 v[94:95], v96 offset1:1
	v_mfma_f32_16x16x32_bf16 v[86:89], v[86:89], v[118:121], v[126:129]
	v_mfma_f32_16x16x32_bf16 v[130:133], v[78:81], v[118:121], v[130:133]
	v_mfma_f32_16x16x32_bf16 v[134:137], v[82:85], v[118:121], v[134:137]
	s_waitcnt lgkmcnt(3)
	v_alignbit_b32 v27, v27, v26, v23
	v_alignbit_b32 v26, v26, v39, v22
	v_alignbit_b32 v25, v39, v25, v21
	v_alignbit_b32 v24, v38, v24, v20
	v_mfma_f32_16x16x32_bf16 v[126:129], v[82:85], v[178:181], v[86:89]
	s_waitcnt lgkmcnt(0)
	s_nop 1
	v_alignbit_b32 v89, v95, v94, v23
	v_alignbit_b32 v88, v94, v99, v22
	v_alignbit_b32 v87, v99, v77, v21
	v_alignbit_b32 v86, v98, v76, v20
	v_mfma_f32_16x16x32_bf16 v[102:105], v[82:85], v[90:93], v[64:67]
	v_mfma_f32_16x16x32_bf16 v[122:125], v[78:81], v[178:181], v[34:37]
	s_nop 1
	v_add_u32_e32 v64, 0x1ad22, v143
	v_add_u32_e32 v66, 0x1ad2a, v143
	v_mfma_f32_16x16x32_bf16 v[94:97], v[24:27], v[90:93], v[68:71]
	v_add_u32_e32 v34, 0x1ad1e, v143
	v_mfma_f32_16x16x32_bf16 v[98:101], v[86:89], v[90:93], v[72:75]
	s_nop 0
	v_add_u32_e32 v68, 0x1acfe, v143
	v_add_u32_e32 v70, 0x1ad02, v143
	v_add_u32_e32 v72, 0x1ad0a, v143
	v_mfma_f32_16x16x32_bf16 v[60:63], v[78:81], v[90:93], v[60:63]
	ds_read_b128 v[90:93], v144 offset:16704
	v_mfma_f32_16x16x32_bf16 v[48:51], v[78:81], v[114:117], v[48:51]
	v_mfma_f32_16x16x32_bf16 v[40:43], v[82:85], v[114:117], v[40:43]
	v_mfma_f32_16x16x32_bf16 v[52:55], v[24:27], v[114:117], v[52:55]
	v_mfma_f32_16x16x32_bf16 v[56:59], v[86:89], v[114:117], v[56:59]
	ds_read_b128 v[114:117], v144 offset:17216
	ds_read_b128 v[36:39], v144 offset:17728
	ds_read_b128 v[118:121], v144 offset:18240
	ds_read2_b32 v[34:35], v34 offset1:1
	ds_read2_b32 v[64:65], v64 offset1:1
	ds_read2_b32 v[66:67], v66 offset1:1
	ds_read2_b32 v[68:69], v68 offset1:1
	ds_read2_b32 v[70:71], v70 offset1:1
	ds_read2_b32 v[72:73], v72 offset1:1
	v_mfma_f32_16x16x32_bf16 v[28:31], v[78:81], v[138:141], v[28:31]
	s_waitcnt lgkmcnt(4)
	v_alignbit_b32 v79, v65, v35, v21
	s_waitcnt lgkmcnt(3)
	v_alignbit_b32 v81, v67, v66, v23
	v_mfma_f32_16x16x32_bf16 v[44:47], v[82:85], v[138:141], v[44:47]
	v_alignbit_b32 v80, v66, v65, v22
	v_alignbit_b32 v78, v64, v34, v20
	v_mfma_f32_16x16x32_bf16 v[110:113], v[24:27], v[138:141], v[110:113]
	v_mfma_f32_16x16x32_bf16 v[106:109], v[86:89], v[138:141], v[106:109]
	v_mfma_f32_16x16x32_bf16 v[130:133], v[24:27], v[178:181], v[130:133]
	v_mfma_f32_16x16x32_bf16 v[134:137], v[86:89], v[178:181], v[134:137]
	s_add_i32 vcc_lo, vcc_lo, 64
	s_addk_i32 s56, 0xff80
	s_waitcnt lgkmcnt(0)
	v_alignbit_b32 v85, v73, v72, v23
	v_alignbit_b32 v84, v72, v71, v22
	v_alignbit_b32 v83, v71, v69, v21
	v_alignbit_b32 v82, v70, v68, v20
	v_add_u32_e32 v142, 0xffffff80, v142
	s_cmp_ge_i32 vcc_lo, s51
	v_add_u32_e32 v32, 0xffffff80, v32
	s_cbranch_scc0 .LBB0_1546
	v_mfma_f32_16x16x32_bf16 v[74:77], v[24:27], v[90:93], v[60:63]
	v_add_u32_e32 v32, s97, v216
	v_mfma_f32_16x16x32_bf16 v[62:65], v[78:81], v[114:117], v[52:55]
	v_mfma_f32_16x16x32_bf16 v[58:61], v[82:85], v[114:117], v[56:59]
	v_mfma_f32_16x16x32_bf16 v[54:57], v[24:27], v[36:39], v[28:31]
	s_nop 2
	v_add_u32_e32 v28, v142, v217
	v_add_u32_e32 v29, s50, v216
	v_mfma_f32_16x16x32_bf16 v[70:73], v[24:27], v[114:117], v[48:51]
	v_mfma_f32_16x16x32_bf16 v[66:69], v[86:89], v[114:117], v[40:43]
	v_mfma_f32_16x16x32_bf16 v[50:53], v[86:89], v[36:39], v[44:47]
	v_mfma_f32_16x16x32_bf16 v[42:45], v[78:81], v[36:39], v[110:113]
	v_mfma_f32_16x16x32_bf16 v[34:37], v[82:85], v[36:39], v[106:109]
	ds_read_b128 v[138:141], v28 offset:17280
	s_nop 1
	ds_read_b128 v[106:109], v28 offset:17792
	v_mfma_f32_16x16x32_bf16 v[46:49], v[24:27], v[118:121], v[122:125]
	ds_read2_b32 v[24:25], v29 offset0:1 offset1:2
	ds_read2_b32 v[26:27], v29 offset0:3 offset1:4
	ds_read2_b32 v[114:115], v32 offset1:1
	ds_read2_b32 v[110:111], v29 offset1:1
	ds_read_b128 v[122:125], v28 offset:18304
	s_waitcnt lgkmcnt(3)
	v_alignbit_b32 v113, v27, v26, v23
	v_mfma_f32_16x16x32_bf16 v[38:41], v[86:89], v[118:121], v[126:129]
	s_nop 2
	ds_read2_b32 v[126:127], v32 offset0:1 offset1:2
	ds_read2_b32 v[116:117], v32 offset0:3 offset1:4
	v_alignbit_b32 v112, v26, v25, v22
	s_waitcnt lgkmcnt(3)
	v_alignbit_b32 v111, v25, v111, v21
	v_mfma_f32_16x16x32_bf16 v[28:31], v[78:81], v[118:121], v[130:133]
	v_alignbit_b32 v110, v24, v110, v20
	v_mfma_f32_16x16x32_bf16 v[24:27], v[82:85], v[118:121], v[134:137]
	s_waitcnt lgkmcnt(0)
	v_alignbit_b32 v117, v117, v116, v23
	v_alignbit_b32 v116, v116, v127, v22
	v_alignbit_b32 v115, v127, v115, v21
	v_alignbit_b32 v114, v126, v114, v20
	v_mov_b64_e32 v[120:121], v[80:81]
	v_mov_b64_e32 v[128:129], v[84:85]
	s_movk_i32 s56, 0x1c0
	v_mov_b32_e32 v32, v225
	s_mov_b32 vcc_lo, s91
	v_mov_b64_e32 v[118:119], v[78:79]
	v_mov_b64_e32 v[126:127], v[82:83]
	s_branch .LBB0_1549
